# adaLN inner loop by hand, 32 rows of ada_w in flight (two batches of 16)
# baseline (speedup 1.0000x reference)
; #define LAS __attribute__((address_space(3)))
; __device__ __forceinline__ void prologue(const __attribute__((address_space(4))) Args& a, ldsp lds, int gw, int NGW, int wave, int lane, const int tid, const int bid, const int G) {
;     ...
;     for (int u = bid; u < 4 * 96; u += G) {
;         const int layer = u / 96, col0 = (u % 96) * 64;
;         const float* Wl = a.ada_w + (size_t)layer * D * NMOD + col0 + lane;
;         float acc[9];
; #pragma unroll
;         for (int j = 0; j < 9; ++j) acc[j] = 0.f;
;         for (int k = wave * 128; k < wave * 128 + 128; k += 16) {
;             float wv[16];
; #pragma unroll
;             for (int q = 0; q < 16; ++q) wv[q] = Wl[(size_t)(k + q) * NMOD];
; #pragma unroll
;             for (int q4 = 0; q4 < 4; ++q4)
; #pragma unroll
;                 for (int j = 0; j < 9; ++j) { const f32x4 s4 = *(const LAS f32x4*)(sc + j * D + k + 4 * q4); acc[j] += s4[0] * wv[4 * q4] + s4[1] * wv[4 * q4 + 1] + s4[2] * wv[4 * q4 + 2] + s4[3] * wv[4 * q4 + 3]; }
.LBB0_1277:
	s_mul_hi_i32 s6, s96, 0x2aaaaaab
	s_lshr_b32 s7, s6, 31
	s_ashr_i32 s6, s6, 4
	s_add_i32 s12, s6, s7
	s_mul_i32 s6, s12, 0x60
	s_sub_i32 s6, s96, s6
	s_lshl_b32 s6, s6, 6
	s_ashr_i32 s7, s6, 31
	s_mul_i32 s14, s12, 0x1800000
	s_lshl_b64 s[8:9], s[6:7], 2
	s_mul_hi_i32 s13, s12, 0x1800000
	s_add_u32 s8, s14, s8
	s_addc_u32 s9, s13, s9
	v_mov_b32_e32 v78, 0
	v_lshl_add_u64 v[76:77], v[74:75], 0, s[8:9]
	s_mov_b32 s8, s3
	s_mov_b32 s9, s1
	v_mov_b32_e32 v79, v78
	v_mov_b32_e32 v84, v78
	v_mov_b32_e32 v85, v78
	v_mov_b32_e32 v82, v78
	v_mov_b32_e32 v83, v78
	v_mov_b32_e32 v80, v78
	v_mov_b32_e32 v81, v78
	v_mov_b32_e32 v92, v78
	v_readfirstlane_b32 s22, v76
	v_readfirstlane_b32 s23, v77
	v_lshlrev_b32_e32 v0, 2, v87
	v_mov_b32_e32 v1, s8
	s_sub_u32 s22, s22, 0x5a000
	s_subb_u32 s23, s23, 0
	s_nop 1
	global_load_dword v2, v0, s[22:23]
	s_add_u32 s22, s22, 0x6000
	s_addc_u32 s23, s23, 0
	global_load_dword v3, v0, s[22:23]
	s_add_u32 s22, s22, 0x6000
	s_addc_u32 s23, s23, 0
	global_load_dword v4, v0, s[22:23]
	s_add_u32 s22, s22, 0x6000
	s_addc_u32 s23, s23, 0
	global_load_dword v5, v0, s[22:23]
	s_add_u32 s22, s22, 0x6000
	s_addc_u32 s23, s23, 0
	global_load_dword v6, v0, s[22:23]
	s_add_u32 s22, s22, 0x6000
	s_addc_u32 s23, s23, 0
	global_load_dword v7, v0, s[22:23]
	s_add_u32 s22, s22, 0x6000
	s_addc_u32 s23, s23, 0
	global_load_dword v8, v0, s[22:23]
	s_add_u32 s22, s22, 0x6000
	s_addc_u32 s23, s23, 0
	global_load_dword v9, v0, s[22:23]
	s_add_u32 s22, s22, 0x6000
	s_addc_u32 s23, s23, 0
	global_load_dword v10, v0, s[22:23]
	s_add_u32 s22, s22, 0x6000
	s_addc_u32 s23, s23, 0
	global_load_dword v11, v0, s[22:23]
	s_add_u32 s22, s22, 0x6000
	s_addc_u32 s23, s23, 0
	global_load_dword v12, v0, s[22:23]
	s_add_u32 s22, s22, 0x6000
	s_addc_u32 s23, s23, 0
	global_load_dword v13, v0, s[22:23]
	s_add_u32 s22, s22, 0x6000
	s_addc_u32 s23, s23, 0
	global_load_dword v14, v0, s[22:23]
	s_add_u32 s22, s22, 0x6000
	s_addc_u32 s23, s23, 0
	global_load_dword v15, v0, s[22:23]
	s_add_u32 s22, s22, 0x6000
	s_addc_u32 s23, s23, 0
	global_load_dword v16, v0, s[22:23]
	s_add_u32 s22, s22, 0x6000
	s_addc_u32 s23, s23, 0
	global_load_dword v17, v0, s[22:23]
	s_add_u32 s22, s22, 0x6000
	s_addc_u32 s23, s23, 0
	ds_read_b128 v[98:101], v1 offset:0
	ds_read_b128 v[102:105], v1 offset:4096
	ds_read_b128 v[106:109], v1 offset:8192
	ds_read_b128 v[110:113], v1 offset:12288
	ds_read_b128 v[114:117], v1 offset:16384
	ds_read_b128 v[118:121], v1 offset:20480
	ds_read_b128 v[122:125], v1 offset:24576
	ds_read_b128 v[126:129], v1 offset:28672
	ds_read_b128 v[130:133], v1 offset:32768
	global_load_dword v34, v0, s[22:23]
	s_add_u32 s22, s22, 0x6000
	s_addc_u32 s23, s23, 0
	global_load_dword v35, v0, s[22:23]
	s_add_u32 s22, s22, 0x6000
	s_addc_u32 s23, s23, 0
	global_load_dword v36, v0, s[22:23]
	s_add_u32 s22, s22, 0x6000
	s_addc_u32 s23, s23, 0
	global_load_dword v37, v0, s[22:23]
	s_add_u32 s22, s22, 0x6000
	s_addc_u32 s23, s23, 0
	global_load_dword v38, v0, s[22:23]
	s_add_u32 s22, s22, 0x6000
	s_addc_u32 s23, s23, 0
	global_load_dword v39, v0, s[22:23]
	s_add_u32 s22, s22, 0x6000
	s_addc_u32 s23, s23, 0
	global_load_dword v40, v0, s[22:23]
	s_add_u32 s22, s22, 0x6000
	s_addc_u32 s23, s23, 0
	global_load_dword v41, v0, s[22:23]
	s_add_u32 s22, s22, 0x6000
	s_addc_u32 s23, s23, 0
	global_load_dword v42, v0, s[22:23]
	s_add_u32 s22, s22, 0x6000
	s_addc_u32 s23, s23, 0
	global_load_dword v43, v0, s[22:23]
	s_add_u32 s22, s22, 0x6000
	s_addc_u32 s23, s23, 0
	global_load_dword v44, v0, s[22:23]
	s_add_u32 s22, s22, 0x6000
	s_addc_u32 s23, s23, 0
	global_load_dword v45, v0, s[22:23]
	s_add_u32 s22, s22, 0x6000
	s_addc_u32 s23, s23, 0
	global_load_dword v46, v0, s[22:23]
	s_add_u32 s22, s22, 0x6000
	s_addc_u32 s23, s23, 0
	global_load_dword v47, v0, s[22:23]
	s_add_u32 s22, s22, 0x6000
	s_addc_u32 s23, s23, 0
	global_load_dword v48, v0, s[22:23]
	s_add_u32 s22, s22, 0x6000
	s_addc_u32 s23, s23, 0
	global_load_dword v49, v0, s[22:23]
	s_add_u32 s22, s22, 0x6000
	s_addc_u32 s23, s23, 0
	v_mov_b64_e32 v[226:227], 0
	v_mov_b64_e32 v[228:229], 0
	v_mov_b64_e32 v[230:231], 0
	v_mov_b64_e32 v[232:233], 0
	v_mov_b64_e32 v[234:235], 0
	v_mov_b64_e32 v[236:237], 0
	v_mov_b64_e32 v[238:239], 0
	v_mov_b64_e32 v[240:241], 0
	v_mov_b64_e32 v[242:243], 0
	s_waitcnt vmcnt(16)
	ds_read_b128 v[134:137], v1 offset:16
	ds_read_b128 v[138:141], v1 offset:4112
	ds_read_b128 v[142:145], v1 offset:8208
	ds_read_b128 v[146:149], v1 offset:12304
	ds_read_b128 v[150:153], v1 offset:16400
	ds_read_b128 v[154:157], v1 offset:20496
	ds_read_b128 v[158:161], v1 offset:24592
	ds_read_b128 v[162:165], v1 offset:28688
	ds_read_b128 v[166:169], v1 offset:32784
	s_waitcnt lgkmcnt(9)
	v_pk_fma_f32 v[226:227], v[98:99], v[2:3], v[226:227]
	v_pk_fma_f32 v[228:229], v[102:103], v[2:3], v[228:229]
	v_pk_fma_f32 v[230:231], v[106:107], v[2:3], v[230:231]
	v_pk_fma_f32 v[232:233], v[110:111], v[2:3], v[232:233]
	v_pk_fma_f32 v[234:235], v[114:115], v[2:3], v[234:235]
	v_pk_fma_f32 v[236:237], v[118:119], v[2:3], v[236:237]
	v_pk_fma_f32 v[238:239], v[122:123], v[2:3], v[238:239]
	v_pk_fma_f32 v[240:241], v[126:127], v[2:3], v[240:241]
	v_pk_fma_f32 v[242:243], v[130:131], v[2:3], v[242:243]
	v_pk_fma_f32 v[226:227], v[100:101], v[4:5], v[226:227]
	v_pk_fma_f32 v[228:229], v[104:105], v[4:5], v[228:229]
	v_pk_fma_f32 v[230:231], v[108:109], v[4:5], v[230:231]
	v_pk_fma_f32 v[232:233], v[112:113], v[4:5], v[232:233]
	v_pk_fma_f32 v[234:235], v[116:117], v[4:5], v[234:235]
	v_pk_fma_f32 v[236:237], v[120:121], v[4:5], v[236:237]
	v_pk_fma_f32 v[238:239], v[124:125], v[4:5], v[238:239]
	v_pk_fma_f32 v[240:241], v[128:129], v[4:5], v[240:241]
	v_pk_fma_f32 v[242:243], v[132:133], v[4:5], v[242:243]
	ds_read_b128 v[98:101], v1 offset:32
	ds_read_b128 v[102:105], v1 offset:4128
	ds_read_b128 v[106:109], v1 offset:8224
	ds_read_b128 v[110:113], v1 offset:12320
	ds_read_b128 v[114:117], v1 offset:16416
	ds_read_b128 v[118:121], v1 offset:20512
	ds_read_b128 v[122:125], v1 offset:24608
	ds_read_b128 v[126:129], v1 offset:28704
	ds_read_b128 v[130:133], v1 offset:32800
	s_waitcnt lgkmcnt(9)
; #define LAS __attribute__((address_space(3)))
; __device__ __forceinline__ void prologue(const __attribute__((address_space(4))) Args& a, ldsp lds, int gw, int NGW, int wave, int lane, const int tid, const int bid, const int G) {
;     ...
;         for (int k = wave * 128; k < wave * 128 + 128; k += 16) {
;             float wv[16];
; #pragma unroll
;             for (int q = 0; q < 16; ++q) wv[q] = Wl[(size_t)(k + q) * NMOD];
; #pragma unroll
;             for (int q4 = 0; q4 < 4; ++q4)
; #pragma unroll
;                 for (int j = 0; j < 9; ++j) { const f32x4 s4 = *(const LAS f32x4*)(sc + j * D + k + 4 * q4); acc[j] += s4[0] * wv[4 * q4] + s4[1] * wv[4 * q4 + 1] + s4[2] * wv[4 * q4 + 2] + s4[3] * wv[4 * q4 + 3]; }
	v_pk_fma_f32 v[226:227], v[134:135], v[6:7], v[226:227]
	v_pk_fma_f32 v[228:229], v[138:139], v[6:7], v[228:229]
	v_pk_fma_f32 v[230:231], v[142:143], v[6:7], v[230:231]
	v_pk_fma_f32 v[232:233], v[146:147], v[6:7], v[232:233]
	v_pk_fma_f32 v[234:235], v[150:151], v[6:7], v[234:235]
	v_pk_fma_f32 v[236:237], v[154:155], v[6:7], v[236:237]
	v_pk_fma_f32 v[238:239], v[158:159], v[6:7], v[238:239]
	v_pk_fma_f32 v[240:241], v[162:163], v[6:7], v[240:241]
	v_pk_fma_f32 v[242:243], v[166:167], v[6:7], v[242:243]
	v_pk_fma_f32 v[226:227], v[136:137], v[8:9], v[226:227]
	v_pk_fma_f32 v[228:229], v[140:141], v[8:9], v[228:229]
	v_pk_fma_f32 v[230:231], v[144:145], v[8:9], v[230:231]
	v_pk_fma_f32 v[232:233], v[148:149], v[8:9], v[232:233]
	v_pk_fma_f32 v[234:235], v[152:153], v[8:9], v[234:235]
	v_pk_fma_f32 v[236:237], v[156:157], v[8:9], v[236:237]
	v_pk_fma_f32 v[238:239], v[160:161], v[8:9], v[238:239]
	v_pk_fma_f32 v[240:241], v[164:165], v[8:9], v[240:241]
	v_pk_fma_f32 v[242:243], v[168:169], v[8:9], v[242:243]
	ds_read_b128 v[134:137], v1 offset:48
	ds_read_b128 v[138:141], v1 offset:4144
	ds_read_b128 v[142:145], v1 offset:8240
	ds_read_b128 v[146:149], v1 offset:12336
	ds_read_b128 v[150:153], v1 offset:16432
	ds_read_b128 v[154:157], v1 offset:20528
	ds_read_b128 v[158:161], v1 offset:24624
	ds_read_b128 v[162:165], v1 offset:28720
	ds_read_b128 v[166:169], v1 offset:32816
	s_waitcnt lgkmcnt(9)
	v_pk_fma_f32 v[226:227], v[98:99], v[10:11], v[226:227]
	v_pk_fma_f32 v[228:229], v[102:103], v[10:11], v[228:229]
	v_pk_fma_f32 v[230:231], v[106:107], v[10:11], v[230:231]
	v_pk_fma_f32 v[232:233], v[110:111], v[10:11], v[232:233]
	v_pk_fma_f32 v[234:235], v[114:115], v[10:11], v[234:235]
	v_pk_fma_f32 v[236:237], v[118:119], v[10:11], v[236:237]
	v_pk_fma_f32 v[238:239], v[122:123], v[10:11], v[238:239]
	v_pk_fma_f32 v[240:241], v[126:127], v[10:11], v[240:241]
	v_pk_fma_f32 v[242:243], v[130:131], v[10:11], v[242:243]
	v_pk_fma_f32 v[226:227], v[100:101], v[12:13], v[226:227]
	v_pk_fma_f32 v[228:229], v[104:105], v[12:13], v[228:229]
	v_pk_fma_f32 v[230:231], v[108:109], v[12:13], v[230:231]
	v_pk_fma_f32 v[232:233], v[112:113], v[12:13], v[232:233]
	v_pk_fma_f32 v[234:235], v[116:117], v[12:13], v[234:235]
	v_pk_fma_f32 v[236:237], v[120:121], v[12:13], v[236:237]
	v_pk_fma_f32 v[238:239], v[124:125], v[12:13], v[238:239]
	v_pk_fma_f32 v[240:241], v[128:129], v[12:13], v[240:241]
	v_pk_fma_f32 v[242:243], v[132:133], v[12:13], v[242:243]
	ds_read_b128 v[98:101], v1 offset:64
	ds_read_b128 v[102:105], v1 offset:4160
	ds_read_b128 v[106:109], v1 offset:8256
	ds_read_b128 v[110:113], v1 offset:12352
	ds_read_b128 v[114:117], v1 offset:16448
	ds_read_b128 v[118:121], v1 offset:20544
	ds_read_b128 v[122:125], v1 offset:24640
	ds_read_b128 v[126:129], v1 offset:28736
	ds_read_b128 v[130:133], v1 offset:32832
	s_waitcnt lgkmcnt(9)
	v_pk_fma_f32 v[226:227], v[134:135], v[14:15], v[226:227]
	v_pk_fma_f32 v[228:229], v[138:139], v[14:15], v[228:229]
	v_pk_fma_f32 v[230:231], v[142:143], v[14:15], v[230:231]
	v_pk_fma_f32 v[232:233], v[146:147], v[14:15], v[232:233]
	v_pk_fma_f32 v[234:235], v[150:151], v[14:15], v[234:235]
	v_pk_fma_f32 v[236:237], v[154:155], v[14:15], v[236:237]
	v_pk_fma_f32 v[238:239], v[158:159], v[14:15], v[238:239]
	v_pk_fma_f32 v[240:241], v[162:163], v[14:15], v[240:241]
	v_pk_fma_f32 v[242:243], v[166:167], v[14:15], v[242:243]
	v_pk_fma_f32 v[226:227], v[136:137], v[16:17], v[226:227]
	v_pk_fma_f32 v[228:229], v[140:141], v[16:17], v[228:229]
	v_pk_fma_f32 v[230:231], v[144:145], v[16:17], v[230:231]
	v_pk_fma_f32 v[232:233], v[148:149], v[16:17], v[232:233]
	v_pk_fma_f32 v[234:235], v[152:153], v[16:17], v[234:235]
	v_pk_fma_f32 v[236:237], v[156:157], v[16:17], v[236:237]
	v_pk_fma_f32 v[238:239], v[160:161], v[16:17], v[238:239]
	v_pk_fma_f32 v[240:241], v[164:165], v[16:17], v[240:241]
	v_pk_fma_f32 v[242:243], v[168:169], v[16:17], v[242:243]
	global_load_dword v2, v0, s[22:23]
	s_add_u32 s22, s22, 0x6000
	s_addc_u32 s23, s23, 0
	global_load_dword v3, v0, s[22:23]
	s_add_u32 s22, s22, 0x6000
	s_addc_u32 s23, s23, 0
	global_load_dword v4, v0, s[22:23]
	s_add_u32 s22, s22, 0x6000
	s_addc_u32 s23, s23, 0
	global_load_dword v5, v0, s[22:23]
	s_add_u32 s22, s22, 0x6000
	s_addc_u32 s23, s23, 0
	global_load_dword v6, v0, s[22:23]
	s_add_u32 s22, s22, 0x6000
	s_addc_u32 s23, s23, 0
	global_load_dword v7, v0, s[22:23]
	s_add_u32 s22, s22, 0x6000
	s_addc_u32 s23, s23, 0
	global_load_dword v8, v0, s[22:23]
	s_add_u32 s22, s22, 0x6000
	s_addc_u32 s23, s23, 0
	global_load_dword v9, v0, s[22:23]
	s_add_u32 s22, s22, 0x6000
	s_addc_u32 s23, s23, 0
	global_load_dword v10, v0, s[22:23]
	s_add_u32 s22, s22, 0x6000
	s_addc_u32 s23, s23, 0
	global_load_dword v11, v0, s[22:23]
	s_add_u32 s22, s22, 0x6000
	s_addc_u32 s23, s23, 0
	global_load_dword v12, v0, s[22:23]
	s_add_u32 s22, s22, 0x6000
	s_addc_u32 s23, s23, 0
	global_load_dword v13, v0, s[22:23]
	s_add_u32 s22, s22, 0x6000
	s_addc_u32 s23, s23, 0
	global_load_dword v14, v0, s[22:23]
	s_add_u32 s22, s22, 0x6000
	s_addc_u32 s23, s23, 0
	global_load_dword v15, v0, s[22:23]
	s_add_u32 s22, s22, 0x6000
	s_addc_u32 s23, s23, 0
	global_load_dword v16, v0, s[22:23]
	s_add_u32 s22, s22, 0x6000
	s_addc_u32 s23, s23, 0
	global_load_dword v17, v0, s[22:23]
	s_add_u32 s22, s22, 0x6000
	s_addc_u32 s23, s23, 0
	s_waitcnt vmcnt(16)
	ds_read_b128 v[134:137], v1 offset:80
	ds_read_b128 v[138:141], v1 offset:4176
	ds_read_b128 v[142:145], v1 offset:8272
	ds_read_b128 v[146:149], v1 offset:12368
	ds_read_b128 v[150:153], v1 offset:16464
	ds_read_b128 v[154:157], v1 offset:20560
	ds_read_b128 v[158:161], v1 offset:24656
	ds_read_b128 v[162:165], v1 offset:28752
	ds_read_b128 v[166:169], v1 offset:32848
	s_waitcnt lgkmcnt(9)
; #define LAS __attribute__((address_space(3)))
; __device__ __forceinline__ void prologue(const __attribute__((address_space(4))) Args& a, ldsp lds, int gw, int NGW, int wave, int lane, const int tid, const int bid, const int G) {
;     ...
;         for (int k = wave * 128; k < wave * 128 + 128; k += 16) {
;             float wv[16];
; #pragma unroll
;             for (int q = 0; q < 16; ++q) wv[q] = Wl[(size_t)(k + q) * NMOD];
; #pragma unroll
;             for (int q4 = 0; q4 < 4; ++q4)
; #pragma unroll
;                 for (int j = 0; j < 9; ++j) { const f32x4 s4 = *(const LAS f32x4*)(sc + j * D + k + 4 * q4); acc[j] += s4[0] * wv[4 * q4] + s4[1] * wv[4 * q4 + 1] + s4[2] * wv[4 * q4 + 2] + s4[3] * wv[4 * q4 + 3]; }
	v_pk_fma_f32 v[226:227], v[98:99], v[34:35], v[226:227]
	v_pk_fma_f32 v[228:229], v[102:103], v[34:35], v[228:229]
	v_pk_fma_f32 v[230:231], v[106:107], v[34:35], v[230:231]
	v_pk_fma_f32 v[232:233], v[110:111], v[34:35], v[232:233]
	v_pk_fma_f32 v[234:235], v[114:115], v[34:35], v[234:235]
	v_pk_fma_f32 v[236:237], v[118:119], v[34:35], v[236:237]
	v_pk_fma_f32 v[238:239], v[122:123], v[34:35], v[238:239]
	v_pk_fma_f32 v[240:241], v[126:127], v[34:35], v[240:241]
	v_pk_fma_f32 v[242:243], v[130:131], v[34:35], v[242:243]
	v_pk_fma_f32 v[226:227], v[100:101], v[36:37], v[226:227]
	v_pk_fma_f32 v[228:229], v[104:105], v[36:37], v[228:229]
	v_pk_fma_f32 v[230:231], v[108:109], v[36:37], v[230:231]
	v_pk_fma_f32 v[232:233], v[112:113], v[36:37], v[232:233]
	v_pk_fma_f32 v[234:235], v[116:117], v[36:37], v[234:235]
	v_pk_fma_f32 v[236:237], v[120:121], v[36:37], v[236:237]
	v_pk_fma_f32 v[238:239], v[124:125], v[36:37], v[238:239]
	v_pk_fma_f32 v[240:241], v[128:129], v[36:37], v[240:241]
	v_pk_fma_f32 v[242:243], v[132:133], v[36:37], v[242:243]
	ds_read_b128 v[98:101], v1 offset:96
	ds_read_b128 v[102:105], v1 offset:4192
	ds_read_b128 v[106:109], v1 offset:8288
	ds_read_b128 v[110:113], v1 offset:12384
	ds_read_b128 v[114:117], v1 offset:16480
	ds_read_b128 v[118:121], v1 offset:20576
	ds_read_b128 v[122:125], v1 offset:24672
	ds_read_b128 v[126:129], v1 offset:28768
	ds_read_b128 v[130:133], v1 offset:32864
	s_waitcnt lgkmcnt(9)
	v_pk_fma_f32 v[226:227], v[134:135], v[38:39], v[226:227]
	v_pk_fma_f32 v[228:229], v[138:139], v[38:39], v[228:229]
	v_pk_fma_f32 v[230:231], v[142:143], v[38:39], v[230:231]
	v_pk_fma_f32 v[232:233], v[146:147], v[38:39], v[232:233]
	v_pk_fma_f32 v[234:235], v[150:151], v[38:39], v[234:235]
	v_pk_fma_f32 v[236:237], v[154:155], v[38:39], v[236:237]
	v_pk_fma_f32 v[238:239], v[158:159], v[38:39], v[238:239]
	v_pk_fma_f32 v[240:241], v[162:163], v[38:39], v[240:241]
	v_pk_fma_f32 v[242:243], v[166:167], v[38:39], v[242:243]
	v_pk_fma_f32 v[226:227], v[136:137], v[40:41], v[226:227]
	v_pk_fma_f32 v[228:229], v[140:141], v[40:41], v[228:229]
	v_pk_fma_f32 v[230:231], v[144:145], v[40:41], v[230:231]
	v_pk_fma_f32 v[232:233], v[148:149], v[40:41], v[232:233]
	v_pk_fma_f32 v[234:235], v[152:153], v[40:41], v[234:235]
	v_pk_fma_f32 v[236:237], v[156:157], v[40:41], v[236:237]
	v_pk_fma_f32 v[238:239], v[160:161], v[40:41], v[238:239]
	v_pk_fma_f32 v[240:241], v[164:165], v[40:41], v[240:241]
	v_pk_fma_f32 v[242:243], v[168:169], v[40:41], v[242:243]
	ds_read_b128 v[134:137], v1 offset:112
	ds_read_b128 v[138:141], v1 offset:4208
	ds_read_b128 v[142:145], v1 offset:8304
	ds_read_b128 v[146:149], v1 offset:12400
	ds_read_b128 v[150:153], v1 offset:16496
	ds_read_b128 v[154:157], v1 offset:20592
	ds_read_b128 v[158:161], v1 offset:24688
	ds_read_b128 v[162:165], v1 offset:28784
	ds_read_b128 v[166:169], v1 offset:32880
	s_waitcnt lgkmcnt(9)
	v_pk_fma_f32 v[226:227], v[98:99], v[42:43], v[226:227]
	v_pk_fma_f32 v[228:229], v[102:103], v[42:43], v[228:229]
	v_pk_fma_f32 v[230:231], v[106:107], v[42:43], v[230:231]
	v_pk_fma_f32 v[232:233], v[110:111], v[42:43], v[232:233]
	v_pk_fma_f32 v[234:235], v[114:115], v[42:43], v[234:235]
	v_pk_fma_f32 v[236:237], v[118:119], v[42:43], v[236:237]
	v_pk_fma_f32 v[238:239], v[122:123], v[42:43], v[238:239]
	v_pk_fma_f32 v[240:241], v[126:127], v[42:43], v[240:241]
	v_pk_fma_f32 v[242:243], v[130:131], v[42:43], v[242:243]
	v_pk_fma_f32 v[226:227], v[100:101], v[44:45], v[226:227]
	v_pk_fma_f32 v[228:229], v[104:105], v[44:45], v[228:229]
	v_pk_fma_f32 v[230:231], v[108:109], v[44:45], v[230:231]
	v_pk_fma_f32 v[232:233], v[112:113], v[44:45], v[232:233]
	v_pk_fma_f32 v[234:235], v[116:117], v[44:45], v[234:235]
	v_pk_fma_f32 v[236:237], v[120:121], v[44:45], v[236:237]
	v_pk_fma_f32 v[238:239], v[124:125], v[44:45], v[238:239]
	v_pk_fma_f32 v[240:241], v[128:129], v[44:45], v[240:241]
	v_pk_fma_f32 v[242:243], v[132:133], v[44:45], v[242:243]
	ds_read_b128 v[98:101], v1 offset:128
	ds_read_b128 v[102:105], v1 offset:4224
	ds_read_b128 v[106:109], v1 offset:8320
	ds_read_b128 v[110:113], v1 offset:12416
	ds_read_b128 v[114:117], v1 offset:16512
	ds_read_b128 v[118:121], v1 offset:20608
	ds_read_b128 v[122:125], v1 offset:24704
	ds_read_b128 v[126:129], v1 offset:28800
	ds_read_b128 v[130:133], v1 offset:32896
	s_waitcnt lgkmcnt(9)
	v_pk_fma_f32 v[226:227], v[134:135], v[46:47], v[226:227]
	v_pk_fma_f32 v[228:229], v[138:139], v[46:47], v[228:229]
	v_pk_fma_f32 v[230:231], v[142:143], v[46:47], v[230:231]
	v_pk_fma_f32 v[232:233], v[146:147], v[46:47], v[232:233]
	v_pk_fma_f32 v[234:235], v[150:151], v[46:47], v[234:235]
	v_pk_fma_f32 v[236:237], v[154:155], v[46:47], v[236:237]
	v_pk_fma_f32 v[238:239], v[158:159], v[46:47], v[238:239]
	v_pk_fma_f32 v[240:241], v[162:163], v[46:47], v[240:241]
	v_pk_fma_f32 v[242:243], v[166:167], v[46:47], v[242:243]
	v_pk_fma_f32 v[226:227], v[136:137], v[48:49], v[226:227]
	v_pk_fma_f32 v[228:229], v[140:141], v[48:49], v[228:229]
	v_pk_fma_f32 v[230:231], v[144:145], v[48:49], v[230:231]
	v_pk_fma_f32 v[232:233], v[148:149], v[48:49], v[232:233]
	v_pk_fma_f32 v[234:235], v[152:153], v[48:49], v[234:235]
	v_pk_fma_f32 v[236:237], v[156:157], v[48:49], v[236:237]
	v_pk_fma_f32 v[238:239], v[160:161], v[48:49], v[238:239]
	v_pk_fma_f32 v[240:241], v[164:165], v[48:49], v[240:241]
	v_pk_fma_f32 v[242:243], v[168:169], v[48:49], v[242:243]
	global_load_dword v34, v0, s[22:23]
	s_add_u32 s22, s22, 0x6000
	s_addc_u32 s23, s23, 0
	global_load_dword v35, v0, s[22:23]
	s_add_u32 s22, s22, 0x6000
	s_addc_u32 s23, s23, 0
	global_load_dword v36, v0, s[22:23]
	s_add_u32 s22, s22, 0x6000
	s_addc_u32 s23, s23, 0
	global_load_dword v37, v0, s[22:23]
	s_add_u32 s22, s22, 0x6000
	s_addc_u32 s23, s23, 0
	global_load_dword v38, v0, s[22:23]
	s_add_u32 s22, s22, 0x6000
	s_addc_u32 s23, s23, 0
	global_load_dword v39, v0, s[22:23]
	s_add_u32 s22, s22, 0x6000
	s_addc_u32 s23, s23, 0
	global_load_dword v40, v0, s[22:23]
	s_add_u32 s22, s22, 0x6000
	s_addc_u32 s23, s23, 0
	global_load_dword v41, v0, s[22:23]
	s_add_u32 s22, s22, 0x6000
	s_addc_u32 s23, s23, 0
	global_load_dword v42, v0, s[22:23]
	s_add_u32 s22, s22, 0x6000
	s_addc_u32 s23, s23, 0
	global_load_dword v43, v0, s[22:23]
	s_add_u32 s22, s22, 0x6000
	s_addc_u32 s23, s23, 0
	global_load_dword v44, v0, s[22:23]
	s_add_u32 s22, s22, 0x6000
	s_addc_u32 s23, s23, 0
	global_load_dword v45, v0, s[22:23]
	s_add_u32 s22, s22, 0x6000
	s_addc_u32 s23, s23, 0
	global_load_dword v46, v0, s[22:23]
	s_add_u32 s22, s22, 0x6000
	s_addc_u32 s23, s23, 0
	global_load_dword v47, v0, s[22:23]
	s_add_u32 s22, s22, 0x6000
	s_addc_u32 s23, s23, 0
	global_load_dword v48, v0, s[22:23]
	s_add_u32 s22, s22, 0x6000
	s_addc_u32 s23, s23, 0
	global_load_dword v49, v0, s[22:23]
	s_add_u32 s22, s22, 0x6000
	s_addc_u32 s23, s23, 0
	s_waitcnt vmcnt(16)
; #define LAS __attribute__((address_space(3)))
; __device__ __forceinline__ void prologue(const __attribute__((address_space(4))) Args& a, ldsp lds, int gw, int NGW, int wave, int lane, const int tid, const int bid, const int G) {
;     ...
;         for (int k = wave * 128; k < wave * 128 + 128; k += 16) {
;             float wv[16];
; #pragma unroll
;             for (int q = 0; q < 16; ++q) wv[q] = Wl[(size_t)(k + q) * NMOD];
; #pragma unroll
;             for (int q4 = 0; q4 < 4; ++q4)
; #pragma unroll
;                 for (int j = 0; j < 9; ++j) { const f32x4 s4 = *(const LAS f32x4*)(sc + j * D + k + 4 * q4); acc[j] += s4[0] * wv[4 * q4] + s4[1] * wv[4 * q4 + 1] + s4[2] * wv[4 * q4 + 2] + s4[3] * wv[4 * q4 + 3]; }
	ds_read_b128 v[134:137], v1 offset:144
	ds_read_b128 v[138:141], v1 offset:4240
	ds_read_b128 v[142:145], v1 offset:8336
	ds_read_b128 v[146:149], v1 offset:12432
	ds_read_b128 v[150:153], v1 offset:16528
	ds_read_b128 v[154:157], v1 offset:20624
	ds_read_b128 v[158:161], v1 offset:24720
	ds_read_b128 v[162:165], v1 offset:28816
	ds_read_b128 v[166:169], v1 offset:32912
	s_waitcnt lgkmcnt(9)
	v_pk_fma_f32 v[226:227], v[98:99], v[2:3], v[226:227]
	v_pk_fma_f32 v[228:229], v[102:103], v[2:3], v[228:229]
	v_pk_fma_f32 v[230:231], v[106:107], v[2:3], v[230:231]
	v_pk_fma_f32 v[232:233], v[110:111], v[2:3], v[232:233]
	v_pk_fma_f32 v[234:235], v[114:115], v[2:3], v[234:235]
	v_pk_fma_f32 v[236:237], v[118:119], v[2:3], v[236:237]
	v_pk_fma_f32 v[238:239], v[122:123], v[2:3], v[238:239]
	v_pk_fma_f32 v[240:241], v[126:127], v[2:3], v[240:241]
	v_pk_fma_f32 v[242:243], v[130:131], v[2:3], v[242:243]
	v_pk_fma_f32 v[226:227], v[100:101], v[4:5], v[226:227]
	v_pk_fma_f32 v[228:229], v[104:105], v[4:5], v[228:229]
	v_pk_fma_f32 v[230:231], v[108:109], v[4:5], v[230:231]
	v_pk_fma_f32 v[232:233], v[112:113], v[4:5], v[232:233]
	v_pk_fma_f32 v[234:235], v[116:117], v[4:5], v[234:235]
	v_pk_fma_f32 v[236:237], v[120:121], v[4:5], v[236:237]
	v_pk_fma_f32 v[238:239], v[124:125], v[4:5], v[238:239]
	v_pk_fma_f32 v[240:241], v[128:129], v[4:5], v[240:241]
	v_pk_fma_f32 v[242:243], v[132:133], v[4:5], v[242:243]
	ds_read_b128 v[98:101], v1 offset:160
	ds_read_b128 v[102:105], v1 offset:4256
	ds_read_b128 v[106:109], v1 offset:8352
	ds_read_b128 v[110:113], v1 offset:12448
	ds_read_b128 v[114:117], v1 offset:16544
	ds_read_b128 v[118:121], v1 offset:20640
	ds_read_b128 v[122:125], v1 offset:24736
	ds_read_b128 v[126:129], v1 offset:28832
	ds_read_b128 v[130:133], v1 offset:32928
	s_waitcnt lgkmcnt(9)
	v_pk_fma_f32 v[226:227], v[134:135], v[6:7], v[226:227]
	v_pk_fma_f32 v[228:229], v[138:139], v[6:7], v[228:229]
	v_pk_fma_f32 v[230:231], v[142:143], v[6:7], v[230:231]
	v_pk_fma_f32 v[232:233], v[146:147], v[6:7], v[232:233]
	v_pk_fma_f32 v[234:235], v[150:151], v[6:7], v[234:235]
	v_pk_fma_f32 v[236:237], v[154:155], v[6:7], v[236:237]
	v_pk_fma_f32 v[238:239], v[158:159], v[6:7], v[238:239]
	v_pk_fma_f32 v[240:241], v[162:163], v[6:7], v[240:241]
	v_pk_fma_f32 v[242:243], v[166:167], v[6:7], v[242:243]
	v_pk_fma_f32 v[226:227], v[136:137], v[8:9], v[226:227]
	v_pk_fma_f32 v[228:229], v[140:141], v[8:9], v[228:229]
	v_pk_fma_f32 v[230:231], v[144:145], v[8:9], v[230:231]
	v_pk_fma_f32 v[232:233], v[148:149], v[8:9], v[232:233]
	v_pk_fma_f32 v[234:235], v[152:153], v[8:9], v[234:235]
	v_pk_fma_f32 v[236:237], v[156:157], v[8:9], v[236:237]
	v_pk_fma_f32 v[238:239], v[160:161], v[8:9], v[238:239]
	v_pk_fma_f32 v[240:241], v[164:165], v[8:9], v[240:241]
	v_pk_fma_f32 v[242:243], v[168:169], v[8:9], v[242:243]
	ds_read_b128 v[134:137], v1 offset:176
	ds_read_b128 v[138:141], v1 offset:4272
	ds_read_b128 v[142:145], v1 offset:8368
	ds_read_b128 v[146:149], v1 offset:12464
	ds_read_b128 v[150:153], v1 offset:16560
	ds_read_b128 v[154:157], v1 offset:20656
	ds_read_b128 v[158:161], v1 offset:24752
	ds_read_b128 v[162:165], v1 offset:28848
	ds_read_b128 v[166:169], v1 offset:32944
	s_waitcnt lgkmcnt(9)
	v_pk_fma_f32 v[226:227], v[98:99], v[10:11], v[226:227]
	v_pk_fma_f32 v[228:229], v[102:103], v[10:11], v[228:229]
	v_pk_fma_f32 v[230:231], v[106:107], v[10:11], v[230:231]
	v_pk_fma_f32 v[232:233], v[110:111], v[10:11], v[232:233]
	v_pk_fma_f32 v[234:235], v[114:115], v[10:11], v[234:235]
	v_pk_fma_f32 v[236:237], v[118:119], v[10:11], v[236:237]
	v_pk_fma_f32 v[238:239], v[122:123], v[10:11], v[238:239]
	v_pk_fma_f32 v[240:241], v[126:127], v[10:11], v[240:241]
	v_pk_fma_f32 v[242:243], v[130:131], v[10:11], v[242:243]
	v_pk_fma_f32 v[226:227], v[100:101], v[12:13], v[226:227]
	v_pk_fma_f32 v[228:229], v[104:105], v[12:13], v[228:229]
	v_pk_fma_f32 v[230:231], v[108:109], v[12:13], v[230:231]
	v_pk_fma_f32 v[232:233], v[112:113], v[12:13], v[232:233]
	v_pk_fma_f32 v[234:235], v[116:117], v[12:13], v[234:235]
	v_pk_fma_f32 v[236:237], v[120:121], v[12:13], v[236:237]
	v_pk_fma_f32 v[238:239], v[124:125], v[12:13], v[238:239]
	v_pk_fma_f32 v[240:241], v[128:129], v[12:13], v[240:241]
	v_pk_fma_f32 v[242:243], v[132:133], v[12:13], v[242:243]
	ds_read_b128 v[98:101], v1 offset:192
	ds_read_b128 v[102:105], v1 offset:4288
	ds_read_b128 v[106:109], v1 offset:8384
	ds_read_b128 v[110:113], v1 offset:12480
	ds_read_b128 v[114:117], v1 offset:16576
	ds_read_b128 v[118:121], v1 offset:20672
	ds_read_b128 v[122:125], v1 offset:24768
	ds_read_b128 v[126:129], v1 offset:28864
	ds_read_b128 v[130:133], v1 offset:32960
	s_waitcnt lgkmcnt(9)
; #define LAS __attribute__((address_space(3)))
; __device__ __forceinline__ void prologue(const __attribute__((address_space(4))) Args& a, ldsp lds, int gw, int NGW, int wave, int lane, const int tid, const int bid, const int G) {
;     ...
;         for (int k = wave * 128; k < wave * 128 + 128; k += 16) {
;             float wv[16];
; #pragma unroll
;             for (int q = 0; q < 16; ++q) wv[q] = Wl[(size_t)(k + q) * NMOD];
; #pragma unroll
;             for (int q4 = 0; q4 < 4; ++q4)
; #pragma unroll
;                 for (int j = 0; j < 9; ++j) { const f32x4 s4 = *(const LAS f32x4*)(sc + j * D + k + 4 * q4); acc[j] += s4[0] * wv[4 * q4] + s4[1] * wv[4 * q4 + 1] + s4[2] * wv[4 * q4 + 2] + s4[3] * wv[4 * q4 + 3]; }
	v_pk_fma_f32 v[226:227], v[134:135], v[14:15], v[226:227]
	v_pk_fma_f32 v[228:229], v[138:139], v[14:15], v[228:229]
	v_pk_fma_f32 v[230:231], v[142:143], v[14:15], v[230:231]
	v_pk_fma_f32 v[232:233], v[146:147], v[14:15], v[232:233]
	v_pk_fma_f32 v[234:235], v[150:151], v[14:15], v[234:235]
	v_pk_fma_f32 v[236:237], v[154:155], v[14:15], v[236:237]
	v_pk_fma_f32 v[238:239], v[158:159], v[14:15], v[238:239]
	v_pk_fma_f32 v[240:241], v[162:163], v[14:15], v[240:241]
	v_pk_fma_f32 v[242:243], v[166:167], v[14:15], v[242:243]
	v_pk_fma_f32 v[226:227], v[136:137], v[16:17], v[226:227]
	v_pk_fma_f32 v[228:229], v[140:141], v[16:17], v[228:229]
	v_pk_fma_f32 v[230:231], v[144:145], v[16:17], v[230:231]
	v_pk_fma_f32 v[232:233], v[148:149], v[16:17], v[232:233]
	v_pk_fma_f32 v[234:235], v[152:153], v[16:17], v[234:235]
	v_pk_fma_f32 v[236:237], v[156:157], v[16:17], v[236:237]
	v_pk_fma_f32 v[238:239], v[160:161], v[16:17], v[238:239]
	v_pk_fma_f32 v[240:241], v[164:165], v[16:17], v[240:241]
	v_pk_fma_f32 v[242:243], v[168:169], v[16:17], v[242:243]
	global_load_dword v2, v0, s[22:23]
	s_add_u32 s22, s22, 0x6000
	s_addc_u32 s23, s23, 0
	global_load_dword v3, v0, s[22:23]
	s_add_u32 s22, s22, 0x6000
	s_addc_u32 s23, s23, 0
	global_load_dword v4, v0, s[22:23]
	s_add_u32 s22, s22, 0x6000
	s_addc_u32 s23, s23, 0
	global_load_dword v5, v0, s[22:23]
	s_add_u32 s22, s22, 0x6000
	s_addc_u32 s23, s23, 0
	global_load_dword v6, v0, s[22:23]
	s_add_u32 s22, s22, 0x6000
	s_addc_u32 s23, s23, 0
	global_load_dword v7, v0, s[22:23]
	s_add_u32 s22, s22, 0x6000
	s_addc_u32 s23, s23, 0
	global_load_dword v8, v0, s[22:23]
	s_add_u32 s22, s22, 0x6000
	s_addc_u32 s23, s23, 0
	global_load_dword v9, v0, s[22:23]
	s_add_u32 s22, s22, 0x6000
	s_addc_u32 s23, s23, 0
	global_load_dword v10, v0, s[22:23]
	s_add_u32 s22, s22, 0x6000
	s_addc_u32 s23, s23, 0
	global_load_dword v11, v0, s[22:23]
	s_add_u32 s22, s22, 0x6000
	s_addc_u32 s23, s23, 0
	global_load_dword v12, v0, s[22:23]
	s_add_u32 s22, s22, 0x6000
	s_addc_u32 s23, s23, 0
	global_load_dword v13, v0, s[22:23]
	s_add_u32 s22, s22, 0x6000
	s_addc_u32 s23, s23, 0
	global_load_dword v14, v0, s[22:23]
	s_add_u32 s22, s22, 0x6000
	s_addc_u32 s23, s23, 0
	global_load_dword v15, v0, s[22:23]
	s_add_u32 s22, s22, 0x6000
	s_addc_u32 s23, s23, 0
	global_load_dword v16, v0, s[22:23]
	s_add_u32 s22, s22, 0x6000
	s_addc_u32 s23, s23, 0
	global_load_dword v17, v0, s[22:23]
	s_add_u32 s22, s22, 0x6000
	s_addc_u32 s23, s23, 0
	s_waitcnt vmcnt(16)
	ds_read_b128 v[134:137], v1 offset:208
	ds_read_b128 v[138:141], v1 offset:4304
	ds_read_b128 v[142:145], v1 offset:8400
	ds_read_b128 v[146:149], v1 offset:12496
	ds_read_b128 v[150:153], v1 offset:16592
	ds_read_b128 v[154:157], v1 offset:20688
	ds_read_b128 v[158:161], v1 offset:24784
	ds_read_b128 v[162:165], v1 offset:28880
	ds_read_b128 v[166:169], v1 offset:32976
	s_waitcnt lgkmcnt(9)
	v_pk_fma_f32 v[226:227], v[98:99], v[34:35], v[226:227]
	v_pk_fma_f32 v[228:229], v[102:103], v[34:35], v[228:229]
	v_pk_fma_f32 v[230:231], v[106:107], v[34:35], v[230:231]
	v_pk_fma_f32 v[232:233], v[110:111], v[34:35], v[232:233]
	v_pk_fma_f32 v[234:235], v[114:115], v[34:35], v[234:235]
	v_pk_fma_f32 v[236:237], v[118:119], v[34:35], v[236:237]
	v_pk_fma_f32 v[238:239], v[122:123], v[34:35], v[238:239]
	v_pk_fma_f32 v[240:241], v[126:127], v[34:35], v[240:241]
	v_pk_fma_f32 v[242:243], v[130:131], v[34:35], v[242:243]
	v_pk_fma_f32 v[226:227], v[100:101], v[36:37], v[226:227]
	v_pk_fma_f32 v[228:229], v[104:105], v[36:37], v[228:229]
	v_pk_fma_f32 v[230:231], v[108:109], v[36:37], v[230:231]
	v_pk_fma_f32 v[232:233], v[112:113], v[36:37], v[232:233]
	v_pk_fma_f32 v[234:235], v[116:117], v[36:37], v[234:235]
	v_pk_fma_f32 v[236:237], v[120:121], v[36:37], v[236:237]
	v_pk_fma_f32 v[238:239], v[124:125], v[36:37], v[238:239]
	v_pk_fma_f32 v[240:241], v[128:129], v[36:37], v[240:241]
	v_pk_fma_f32 v[242:243], v[132:133], v[36:37], v[242:243]
	ds_read_b128 v[98:101], v1 offset:224
	ds_read_b128 v[102:105], v1 offset:4320
	ds_read_b128 v[106:109], v1 offset:8416
	ds_read_b128 v[110:113], v1 offset:12512
	ds_read_b128 v[114:117], v1 offset:16608
	ds_read_b128 v[118:121], v1 offset:20704
	ds_read_b128 v[122:125], v1 offset:24800
	ds_read_b128 v[126:129], v1 offset:28896
	ds_read_b128 v[130:133], v1 offset:32992
	s_waitcnt lgkmcnt(9)
	v_pk_fma_f32 v[226:227], v[134:135], v[38:39], v[226:227]
	v_pk_fma_f32 v[228:229], v[138:139], v[38:39], v[228:229]
	v_pk_fma_f32 v[230:231], v[142:143], v[38:39], v[230:231]
	v_pk_fma_f32 v[232:233], v[146:147], v[38:39], v[232:233]
	v_pk_fma_f32 v[234:235], v[150:151], v[38:39], v[234:235]
	v_pk_fma_f32 v[236:237], v[154:155], v[38:39], v[236:237]
	v_pk_fma_f32 v[238:239], v[158:159], v[38:39], v[238:239]
	v_pk_fma_f32 v[240:241], v[162:163], v[38:39], v[240:241]
	v_pk_fma_f32 v[242:243], v[166:167], v[38:39], v[242:243]
	v_pk_fma_f32 v[226:227], v[136:137], v[40:41], v[226:227]
	v_pk_fma_f32 v[228:229], v[140:141], v[40:41], v[228:229]
	v_pk_fma_f32 v[230:231], v[144:145], v[40:41], v[230:231]
	v_pk_fma_f32 v[232:233], v[148:149], v[40:41], v[232:233]
	v_pk_fma_f32 v[234:235], v[152:153], v[40:41], v[234:235]
	v_pk_fma_f32 v[236:237], v[156:157], v[40:41], v[236:237]
	v_pk_fma_f32 v[238:239], v[160:161], v[40:41], v[238:239]
	v_pk_fma_f32 v[240:241], v[164:165], v[40:41], v[240:241]
	v_pk_fma_f32 v[242:243], v[168:169], v[40:41], v[242:243]
	ds_read_b128 v[134:137], v1 offset:240
	ds_read_b128 v[138:141], v1 offset:4336
	ds_read_b128 v[142:145], v1 offset:8432
	ds_read_b128 v[146:149], v1 offset:12528
	ds_read_b128 v[150:153], v1 offset:16624
	ds_read_b128 v[154:157], v1 offset:20720
	ds_read_b128 v[158:161], v1 offset:24816
	ds_read_b128 v[162:165], v1 offset:28912
	ds_read_b128 v[166:169], v1 offset:33008
	s_waitcnt lgkmcnt(9)
; #define LAS __attribute__((address_space(3)))
; __device__ __forceinline__ void prologue(const __attribute__((address_space(4))) Args& a, ldsp lds, int gw, int NGW, int wave, int lane, const int tid, const int bid, const int G) {
;     ...
;         for (int k = wave * 128; k < wave * 128 + 128; k += 16) {
;             float wv[16];
; #pragma unroll
;             for (int q = 0; q < 16; ++q) wv[q] = Wl[(size_t)(k + q) * NMOD];
; #pragma unroll
;             for (int q4 = 0; q4 < 4; ++q4)
; #pragma unroll
;                 for (int j = 0; j < 9; ++j) { const f32x4 s4 = *(const LAS f32x4*)(sc + j * D + k + 4 * q4); acc[j] += s4[0] * wv[4 * q4] + s4[1] * wv[4 * q4 + 1] + s4[2] * wv[4 * q4 + 2] + s4[3] * wv[4 * q4 + 3]; }
	v_pk_fma_f32 v[226:227], v[98:99], v[42:43], v[226:227]
	v_pk_fma_f32 v[228:229], v[102:103], v[42:43], v[228:229]
	v_pk_fma_f32 v[230:231], v[106:107], v[42:43], v[230:231]
	v_pk_fma_f32 v[232:233], v[110:111], v[42:43], v[232:233]
	v_pk_fma_f32 v[234:235], v[114:115], v[42:43], v[234:235]
	v_pk_fma_f32 v[236:237], v[118:119], v[42:43], v[236:237]
	v_pk_fma_f32 v[238:239], v[122:123], v[42:43], v[238:239]
	v_pk_fma_f32 v[240:241], v[126:127], v[42:43], v[240:241]
	v_pk_fma_f32 v[242:243], v[130:131], v[42:43], v[242:243]
	v_pk_fma_f32 v[226:227], v[100:101], v[44:45], v[226:227]
	v_pk_fma_f32 v[228:229], v[104:105], v[44:45], v[228:229]
	v_pk_fma_f32 v[230:231], v[108:109], v[44:45], v[230:231]
	v_pk_fma_f32 v[232:233], v[112:113], v[44:45], v[232:233]
	v_pk_fma_f32 v[234:235], v[116:117], v[44:45], v[234:235]
	v_pk_fma_f32 v[236:237], v[120:121], v[44:45], v[236:237]
	v_pk_fma_f32 v[238:239], v[124:125], v[44:45], v[238:239]
	v_pk_fma_f32 v[240:241], v[128:129], v[44:45], v[240:241]
	v_pk_fma_f32 v[242:243], v[132:133], v[44:45], v[242:243]
	ds_read_b128 v[98:101], v1 offset:256
	ds_read_b128 v[102:105], v1 offset:4352
	ds_read_b128 v[106:109], v1 offset:8448
	ds_read_b128 v[110:113], v1 offset:12544
	ds_read_b128 v[114:117], v1 offset:16640
	ds_read_b128 v[118:121], v1 offset:20736
	ds_read_b128 v[122:125], v1 offset:24832
	ds_read_b128 v[126:129], v1 offset:28928
	ds_read_b128 v[130:133], v1 offset:33024
	s_waitcnt lgkmcnt(9)
	v_pk_fma_f32 v[226:227], v[134:135], v[46:47], v[226:227]
	v_pk_fma_f32 v[228:229], v[138:139], v[46:47], v[228:229]
	v_pk_fma_f32 v[230:231], v[142:143], v[46:47], v[230:231]
	v_pk_fma_f32 v[232:233], v[146:147], v[46:47], v[232:233]
	v_pk_fma_f32 v[234:235], v[150:151], v[46:47], v[234:235]
	v_pk_fma_f32 v[236:237], v[154:155], v[46:47], v[236:237]
	v_pk_fma_f32 v[238:239], v[158:159], v[46:47], v[238:239]
	v_pk_fma_f32 v[240:241], v[162:163], v[46:47], v[240:241]
	v_pk_fma_f32 v[242:243], v[166:167], v[46:47], v[242:243]
	v_pk_fma_f32 v[226:227], v[136:137], v[48:49], v[226:227]
	v_pk_fma_f32 v[228:229], v[140:141], v[48:49], v[228:229]
	v_pk_fma_f32 v[230:231], v[144:145], v[48:49], v[230:231]
	v_pk_fma_f32 v[232:233], v[148:149], v[48:49], v[232:233]
	v_pk_fma_f32 v[234:235], v[152:153], v[48:49], v[234:235]
	v_pk_fma_f32 v[236:237], v[156:157], v[48:49], v[236:237]
	v_pk_fma_f32 v[238:239], v[160:161], v[48:49], v[238:239]
	v_pk_fma_f32 v[240:241], v[164:165], v[48:49], v[240:241]
	v_pk_fma_f32 v[242:243], v[168:169], v[48:49], v[242:243]
	global_load_dword v34, v0, s[22:23]
	s_add_u32 s22, s22, 0x6000
	s_addc_u32 s23, s23, 0
	global_load_dword v35, v0, s[22:23]
	s_add_u32 s22, s22, 0x6000
	s_addc_u32 s23, s23, 0
	global_load_dword v36, v0, s[22:23]
	s_add_u32 s22, s22, 0x6000
	s_addc_u32 s23, s23, 0
	global_load_dword v37, v0, s[22:23]
	s_add_u32 s22, s22, 0x6000
	s_addc_u32 s23, s23, 0
	global_load_dword v38, v0, s[22:23]
	s_add_u32 s22, s22, 0x6000
	s_addc_u32 s23, s23, 0
	global_load_dword v39, v0, s[22:23]
	s_add_u32 s22, s22, 0x6000
	s_addc_u32 s23, s23, 0
	global_load_dword v40, v0, s[22:23]
	s_add_u32 s22, s22, 0x6000
	s_addc_u32 s23, s23, 0
	global_load_dword v41, v0, s[22:23]
	s_add_u32 s22, s22, 0x6000
	s_addc_u32 s23, s23, 0
	global_load_dword v42, v0, s[22:23]
	s_add_u32 s22, s22, 0x6000
	s_addc_u32 s23, s23, 0
	global_load_dword v43, v0, s[22:23]
	s_add_u32 s22, s22, 0x6000
	s_addc_u32 s23, s23, 0
	global_load_dword v44, v0, s[22:23]
	s_add_u32 s22, s22, 0x6000
	s_addc_u32 s23, s23, 0
	global_load_dword v45, v0, s[22:23]
	s_add_u32 s22, s22, 0x6000
	s_addc_u32 s23, s23, 0
	global_load_dword v46, v0, s[22:23]
	s_add_u32 s22, s22, 0x6000
	s_addc_u32 s23, s23, 0
	global_load_dword v47, v0, s[22:23]
	s_add_u32 s22, s22, 0x6000
	s_addc_u32 s23, s23, 0
	global_load_dword v48, v0, s[22:23]
	s_add_u32 s22, s22, 0x6000
	s_addc_u32 s23, s23, 0
	global_load_dword v49, v0, s[22:23]
	s_add_u32 s22, s22, 0x6000
	s_addc_u32 s23, s23, 0
	s_waitcnt vmcnt(16)
	ds_read_b128 v[134:137], v1 offset:272
	ds_read_b128 v[138:141], v1 offset:4368
	ds_read_b128 v[142:145], v1 offset:8464
	ds_read_b128 v[146:149], v1 offset:12560
	ds_read_b128 v[150:153], v1 offset:16656
	ds_read_b128 v[154:157], v1 offset:20752
	ds_read_b128 v[158:161], v1 offset:24848
	ds_read_b128 v[162:165], v1 offset:28944
	ds_read_b128 v[166:169], v1 offset:33040
	s_waitcnt lgkmcnt(9)
	v_pk_fma_f32 v[226:227], v[98:99], v[2:3], v[226:227]
	v_pk_fma_f32 v[228:229], v[102:103], v[2:3], v[228:229]
	v_pk_fma_f32 v[230:231], v[106:107], v[2:3], v[230:231]
	v_pk_fma_f32 v[232:233], v[110:111], v[2:3], v[232:233]
	v_pk_fma_f32 v[234:235], v[114:115], v[2:3], v[234:235]
	v_pk_fma_f32 v[236:237], v[118:119], v[2:3], v[236:237]
	v_pk_fma_f32 v[238:239], v[122:123], v[2:3], v[238:239]
	v_pk_fma_f32 v[240:241], v[126:127], v[2:3], v[240:241]
	v_pk_fma_f32 v[242:243], v[130:131], v[2:3], v[242:243]
	v_pk_fma_f32 v[226:227], v[100:101], v[4:5], v[226:227]
	v_pk_fma_f32 v[228:229], v[104:105], v[4:5], v[228:229]
	v_pk_fma_f32 v[230:231], v[108:109], v[4:5], v[230:231]
	v_pk_fma_f32 v[232:233], v[112:113], v[4:5], v[232:233]
	v_pk_fma_f32 v[234:235], v[116:117], v[4:5], v[234:235]
	v_pk_fma_f32 v[236:237], v[120:121], v[4:5], v[236:237]
	v_pk_fma_f32 v[238:239], v[124:125], v[4:5], v[238:239]
	v_pk_fma_f32 v[240:241], v[128:129], v[4:5], v[240:241]
	v_pk_fma_f32 v[242:243], v[132:133], v[4:5], v[242:243]
	ds_read_b128 v[98:101], v1 offset:288
	ds_read_b128 v[102:105], v1 offset:4384
	ds_read_b128 v[106:109], v1 offset:8480
	ds_read_b128 v[110:113], v1 offset:12576
	ds_read_b128 v[114:117], v1 offset:16672
	ds_read_b128 v[118:121], v1 offset:20768
	ds_read_b128 v[122:125], v1 offset:24864
	ds_read_b128 v[126:129], v1 offset:28960
	ds_read_b128 v[130:133], v1 offset:33056
	s_waitcnt lgkmcnt(9)
; #define LAS __attribute__((address_space(3)))
; __device__ __forceinline__ void prologue(const __attribute__((address_space(4))) Args& a, ldsp lds, int gw, int NGW, int wave, int lane, const int tid, const int bid, const int G) {
;     ...
;         for (int k = wave * 128; k < wave * 128 + 128; k += 16) {
;             float wv[16];
; #pragma unroll
;             for (int q = 0; q < 16; ++q) wv[q] = Wl[(size_t)(k + q) * NMOD];
; #pragma unroll
;             for (int q4 = 0; q4 < 4; ++q4)
; #pragma unroll
;                 for (int j = 0; j < 9; ++j) { const f32x4 s4 = *(const LAS f32x4*)(sc + j * D + k + 4 * q4); acc[j] += s4[0] * wv[4 * q4] + s4[1] * wv[4 * q4 + 1] + s4[2] * wv[4 * q4 + 2] + s4[3] * wv[4 * q4 + 3]; }
	v_pk_fma_f32 v[226:227], v[134:135], v[6:7], v[226:227]
	v_pk_fma_f32 v[228:229], v[138:139], v[6:7], v[228:229]
	v_pk_fma_f32 v[230:231], v[142:143], v[6:7], v[230:231]
	v_pk_fma_f32 v[232:233], v[146:147], v[6:7], v[232:233]
	v_pk_fma_f32 v[234:235], v[150:151], v[6:7], v[234:235]
	v_pk_fma_f32 v[236:237], v[154:155], v[6:7], v[236:237]
	v_pk_fma_f32 v[238:239], v[158:159], v[6:7], v[238:239]
	v_pk_fma_f32 v[240:241], v[162:163], v[6:7], v[240:241]
	v_pk_fma_f32 v[242:243], v[166:167], v[6:7], v[242:243]
	v_pk_fma_f32 v[226:227], v[136:137], v[8:9], v[226:227]
	v_pk_fma_f32 v[228:229], v[140:141], v[8:9], v[228:229]
	v_pk_fma_f32 v[230:231], v[144:145], v[8:9], v[230:231]
	v_pk_fma_f32 v[232:233], v[148:149], v[8:9], v[232:233]
	v_pk_fma_f32 v[234:235], v[152:153], v[8:9], v[234:235]
	v_pk_fma_f32 v[236:237], v[156:157], v[8:9], v[236:237]
	v_pk_fma_f32 v[238:239], v[160:161], v[8:9], v[238:239]
	v_pk_fma_f32 v[240:241], v[164:165], v[8:9], v[240:241]
	v_pk_fma_f32 v[242:243], v[168:169], v[8:9], v[242:243]
	ds_read_b128 v[134:137], v1 offset:304
	ds_read_b128 v[138:141], v1 offset:4400
	ds_read_b128 v[142:145], v1 offset:8496
	ds_read_b128 v[146:149], v1 offset:12592
	ds_read_b128 v[150:153], v1 offset:16688
	ds_read_b128 v[154:157], v1 offset:20784
	ds_read_b128 v[158:161], v1 offset:24880
	ds_read_b128 v[162:165], v1 offset:28976
	ds_read_b128 v[166:169], v1 offset:33072
	s_waitcnt lgkmcnt(9)
	v_pk_fma_f32 v[226:227], v[98:99], v[10:11], v[226:227]
	v_pk_fma_f32 v[228:229], v[102:103], v[10:11], v[228:229]
	v_pk_fma_f32 v[230:231], v[106:107], v[10:11], v[230:231]
	v_pk_fma_f32 v[232:233], v[110:111], v[10:11], v[232:233]
	v_pk_fma_f32 v[234:235], v[114:115], v[10:11], v[234:235]
	v_pk_fma_f32 v[236:237], v[118:119], v[10:11], v[236:237]
	v_pk_fma_f32 v[238:239], v[122:123], v[10:11], v[238:239]
	v_pk_fma_f32 v[240:241], v[126:127], v[10:11], v[240:241]
	v_pk_fma_f32 v[242:243], v[130:131], v[10:11], v[242:243]
	v_pk_fma_f32 v[226:227], v[100:101], v[12:13], v[226:227]
	v_pk_fma_f32 v[228:229], v[104:105], v[12:13], v[228:229]
	v_pk_fma_f32 v[230:231], v[108:109], v[12:13], v[230:231]
	v_pk_fma_f32 v[232:233], v[112:113], v[12:13], v[232:233]
	v_pk_fma_f32 v[234:235], v[116:117], v[12:13], v[234:235]
	v_pk_fma_f32 v[236:237], v[120:121], v[12:13], v[236:237]
	v_pk_fma_f32 v[238:239], v[124:125], v[12:13], v[238:239]
	v_pk_fma_f32 v[240:241], v[128:129], v[12:13], v[240:241]
	v_pk_fma_f32 v[242:243], v[132:133], v[12:13], v[242:243]
	ds_read_b128 v[98:101], v1 offset:320
	ds_read_b128 v[102:105], v1 offset:4416
	ds_read_b128 v[106:109], v1 offset:8512
	ds_read_b128 v[110:113], v1 offset:12608
	ds_read_b128 v[114:117], v1 offset:16704
	ds_read_b128 v[118:121], v1 offset:20800
	ds_read_b128 v[122:125], v1 offset:24896
	ds_read_b128 v[126:129], v1 offset:28992
	ds_read_b128 v[130:133], v1 offset:33088
	s_waitcnt lgkmcnt(9)
	v_pk_fma_f32 v[226:227], v[134:135], v[14:15], v[226:227]
	v_pk_fma_f32 v[228:229], v[138:139], v[14:15], v[228:229]
	v_pk_fma_f32 v[230:231], v[142:143], v[14:15], v[230:231]
	v_pk_fma_f32 v[232:233], v[146:147], v[14:15], v[232:233]
	v_pk_fma_f32 v[234:235], v[150:151], v[14:15], v[234:235]
	v_pk_fma_f32 v[236:237], v[154:155], v[14:15], v[236:237]
	v_pk_fma_f32 v[238:239], v[158:159], v[14:15], v[238:239]
	v_pk_fma_f32 v[240:241], v[162:163], v[14:15], v[240:241]
	v_pk_fma_f32 v[242:243], v[166:167], v[14:15], v[242:243]
	v_pk_fma_f32 v[226:227], v[136:137], v[16:17], v[226:227]
	v_pk_fma_f32 v[228:229], v[140:141], v[16:17], v[228:229]
	v_pk_fma_f32 v[230:231], v[144:145], v[16:17], v[230:231]
	v_pk_fma_f32 v[232:233], v[148:149], v[16:17], v[232:233]
	v_pk_fma_f32 v[234:235], v[152:153], v[16:17], v[234:235]
	v_pk_fma_f32 v[236:237], v[156:157], v[16:17], v[236:237]
	v_pk_fma_f32 v[238:239], v[160:161], v[16:17], v[238:239]
	v_pk_fma_f32 v[240:241], v[164:165], v[16:17], v[240:241]
	v_pk_fma_f32 v[242:243], v[168:169], v[16:17], v[242:243]
	global_load_dword v2, v0, s[22:23]
	s_add_u32 s22, s22, 0x6000
	s_addc_u32 s23, s23, 0
	global_load_dword v3, v0, s[22:23]
	s_add_u32 s22, s22, 0x6000
	s_addc_u32 s23, s23, 0
	global_load_dword v4, v0, s[22:23]
	s_add_u32 s22, s22, 0x6000
	s_addc_u32 s23, s23, 0
	global_load_dword v5, v0, s[22:23]
	s_add_u32 s22, s22, 0x6000
	s_addc_u32 s23, s23, 0
	global_load_dword v6, v0, s[22:23]
	s_add_u32 s22, s22, 0x6000
	s_addc_u32 s23, s23, 0
	global_load_dword v7, v0, s[22:23]
	s_add_u32 s22, s22, 0x6000
	s_addc_u32 s23, s23, 0
	global_load_dword v8, v0, s[22:23]
	s_add_u32 s22, s22, 0x6000
	s_addc_u32 s23, s23, 0
	global_load_dword v9, v0, s[22:23]
	s_add_u32 s22, s22, 0x6000
	s_addc_u32 s23, s23, 0
	global_load_dword v10, v0, s[22:23]
	s_add_u32 s22, s22, 0x6000
	s_addc_u32 s23, s23, 0
	global_load_dword v11, v0, s[22:23]
	s_add_u32 s22, s22, 0x6000
	s_addc_u32 s23, s23, 0
	global_load_dword v12, v0, s[22:23]
	s_add_u32 s22, s22, 0x6000
	s_addc_u32 s23, s23, 0
	global_load_dword v13, v0, s[22:23]
	s_add_u32 s22, s22, 0x6000
	s_addc_u32 s23, s23, 0
	global_load_dword v14, v0, s[22:23]
	s_add_u32 s22, s22, 0x6000
	s_addc_u32 s23, s23, 0
	global_load_dword v15, v0, s[22:23]
	s_add_u32 s22, s22, 0x6000
	s_addc_u32 s23, s23, 0
	global_load_dword v16, v0, s[22:23]
	s_add_u32 s22, s22, 0x6000
	s_addc_u32 s23, s23, 0
	global_load_dword v17, v0, s[22:23]
	s_add_u32 s22, s22, 0x6000
	s_addc_u32 s23, s23, 0
	s_waitcnt vmcnt(16)
	ds_read_b128 v[134:137], v1 offset:336
	ds_read_b128 v[138:141], v1 offset:4432
	ds_read_b128 v[142:145], v1 offset:8528
	ds_read_b128 v[146:149], v1 offset:12624
	ds_read_b128 v[150:153], v1 offset:16720
	ds_read_b128 v[154:157], v1 offset:20816
	ds_read_b128 v[158:161], v1 offset:24912
	ds_read_b128 v[162:165], v1 offset:29008
	ds_read_b128 v[166:169], v1 offset:33104
	s_waitcnt lgkmcnt(9)
; #define LAS __attribute__((address_space(3)))
; __device__ __forceinline__ void prologue(const __attribute__((address_space(4))) Args& a, ldsp lds, int gw, int NGW, int wave, int lane, const int tid, const int bid, const int G) {
;     ...
;         for (int k = wave * 128; k < wave * 128 + 128; k += 16) {
;             float wv[16];
; #pragma unroll
;             for (int q = 0; q < 16; ++q) wv[q] = Wl[(size_t)(k + q) * NMOD];
; #pragma unroll
;             for (int q4 = 0; q4 < 4; ++q4)
; #pragma unroll
;                 for (int j = 0; j < 9; ++j) { const f32x4 s4 = *(const LAS f32x4*)(sc + j * D + k + 4 * q4); acc[j] += s4[0] * wv[4 * q4] + s4[1] * wv[4 * q4 + 1] + s4[2] * wv[4 * q4 + 2] + s4[3] * wv[4 * q4 + 3]; }
	v_pk_fma_f32 v[226:227], v[98:99], v[34:35], v[226:227]
	v_pk_fma_f32 v[228:229], v[102:103], v[34:35], v[228:229]
	v_pk_fma_f32 v[230:231], v[106:107], v[34:35], v[230:231]
	v_pk_fma_f32 v[232:233], v[110:111], v[34:35], v[232:233]
	v_pk_fma_f32 v[234:235], v[114:115], v[34:35], v[234:235]
	v_pk_fma_f32 v[236:237], v[118:119], v[34:35], v[236:237]
	v_pk_fma_f32 v[238:239], v[122:123], v[34:35], v[238:239]
	v_pk_fma_f32 v[240:241], v[126:127], v[34:35], v[240:241]
	v_pk_fma_f32 v[242:243], v[130:131], v[34:35], v[242:243]
	v_pk_fma_f32 v[226:227], v[100:101], v[36:37], v[226:227]
	v_pk_fma_f32 v[228:229], v[104:105], v[36:37], v[228:229]
	v_pk_fma_f32 v[230:231], v[108:109], v[36:37], v[230:231]
	v_pk_fma_f32 v[232:233], v[112:113], v[36:37], v[232:233]
	v_pk_fma_f32 v[234:235], v[116:117], v[36:37], v[234:235]
	v_pk_fma_f32 v[236:237], v[120:121], v[36:37], v[236:237]
	v_pk_fma_f32 v[238:239], v[124:125], v[36:37], v[238:239]
	v_pk_fma_f32 v[240:241], v[128:129], v[36:37], v[240:241]
	v_pk_fma_f32 v[242:243], v[132:133], v[36:37], v[242:243]
	ds_read_b128 v[98:101], v1 offset:352
	ds_read_b128 v[102:105], v1 offset:4448
	ds_read_b128 v[106:109], v1 offset:8544
	ds_read_b128 v[110:113], v1 offset:12640
	ds_read_b128 v[114:117], v1 offset:16736
	ds_read_b128 v[118:121], v1 offset:20832
	ds_read_b128 v[122:125], v1 offset:24928
	ds_read_b128 v[126:129], v1 offset:29024
	ds_read_b128 v[130:133], v1 offset:33120
	s_waitcnt lgkmcnt(9)
	v_pk_fma_f32 v[226:227], v[134:135], v[38:39], v[226:227]
	v_pk_fma_f32 v[228:229], v[138:139], v[38:39], v[228:229]
	v_pk_fma_f32 v[230:231], v[142:143], v[38:39], v[230:231]
	v_pk_fma_f32 v[232:233], v[146:147], v[38:39], v[232:233]
	v_pk_fma_f32 v[234:235], v[150:151], v[38:39], v[234:235]
	v_pk_fma_f32 v[236:237], v[154:155], v[38:39], v[236:237]
	v_pk_fma_f32 v[238:239], v[158:159], v[38:39], v[238:239]
	v_pk_fma_f32 v[240:241], v[162:163], v[38:39], v[240:241]
	v_pk_fma_f32 v[242:243], v[166:167], v[38:39], v[242:243]
	v_pk_fma_f32 v[226:227], v[136:137], v[40:41], v[226:227]
	v_pk_fma_f32 v[228:229], v[140:141], v[40:41], v[228:229]
	v_pk_fma_f32 v[230:231], v[144:145], v[40:41], v[230:231]
	v_pk_fma_f32 v[232:233], v[148:149], v[40:41], v[232:233]
	v_pk_fma_f32 v[234:235], v[152:153], v[40:41], v[234:235]
	v_pk_fma_f32 v[236:237], v[156:157], v[40:41], v[236:237]
	v_pk_fma_f32 v[238:239], v[160:161], v[40:41], v[238:239]
	v_pk_fma_f32 v[240:241], v[164:165], v[40:41], v[240:241]
	v_pk_fma_f32 v[242:243], v[168:169], v[40:41], v[242:243]
	ds_read_b128 v[134:137], v1 offset:368
	ds_read_b128 v[138:141], v1 offset:4464
	ds_read_b128 v[142:145], v1 offset:8560
	ds_read_b128 v[146:149], v1 offset:12656
	ds_read_b128 v[150:153], v1 offset:16752
	ds_read_b128 v[154:157], v1 offset:20848
	ds_read_b128 v[158:161], v1 offset:24944
	ds_read_b128 v[162:165], v1 offset:29040
	ds_read_b128 v[166:169], v1 offset:33136
	s_waitcnt lgkmcnt(9)
	v_pk_fma_f32 v[226:227], v[98:99], v[42:43], v[226:227]
	v_pk_fma_f32 v[228:229], v[102:103], v[42:43], v[228:229]
	v_pk_fma_f32 v[230:231], v[106:107], v[42:43], v[230:231]
	v_pk_fma_f32 v[232:233], v[110:111], v[42:43], v[232:233]
	v_pk_fma_f32 v[234:235], v[114:115], v[42:43], v[234:235]
	v_pk_fma_f32 v[236:237], v[118:119], v[42:43], v[236:237]
	v_pk_fma_f32 v[238:239], v[122:123], v[42:43], v[238:239]
	v_pk_fma_f32 v[240:241], v[126:127], v[42:43], v[240:241]
	v_pk_fma_f32 v[242:243], v[130:131], v[42:43], v[242:243]
	v_pk_fma_f32 v[226:227], v[100:101], v[44:45], v[226:227]
	v_pk_fma_f32 v[228:229], v[104:105], v[44:45], v[228:229]
	v_pk_fma_f32 v[230:231], v[108:109], v[44:45], v[230:231]
	v_pk_fma_f32 v[232:233], v[112:113], v[44:45], v[232:233]
	v_pk_fma_f32 v[234:235], v[116:117], v[44:45], v[234:235]
	v_pk_fma_f32 v[236:237], v[120:121], v[44:45], v[236:237]
	v_pk_fma_f32 v[238:239], v[124:125], v[44:45], v[238:239]
	v_pk_fma_f32 v[240:241], v[128:129], v[44:45], v[240:241]
	v_pk_fma_f32 v[242:243], v[132:133], v[44:45], v[242:243]
	ds_read_b128 v[98:101], v1 offset:384
	ds_read_b128 v[102:105], v1 offset:4480
	ds_read_b128 v[106:109], v1 offset:8576
	ds_read_b128 v[110:113], v1 offset:12672
	ds_read_b128 v[114:117], v1 offset:16768
	ds_read_b128 v[118:121], v1 offset:20864
	ds_read_b128 v[122:125], v1 offset:24960
	ds_read_b128 v[126:129], v1 offset:29056
	ds_read_b128 v[130:133], v1 offset:33152
	s_waitcnt lgkmcnt(9)
	v_pk_fma_f32 v[226:227], v[134:135], v[46:47], v[226:227]
	v_pk_fma_f32 v[228:229], v[138:139], v[46:47], v[228:229]
	v_pk_fma_f32 v[230:231], v[142:143], v[46:47], v[230:231]
	v_pk_fma_f32 v[232:233], v[146:147], v[46:47], v[232:233]
	v_pk_fma_f32 v[234:235], v[150:151], v[46:47], v[234:235]
	v_pk_fma_f32 v[236:237], v[154:155], v[46:47], v[236:237]
	v_pk_fma_f32 v[238:239], v[158:159], v[46:47], v[238:239]
	v_pk_fma_f32 v[240:241], v[162:163], v[46:47], v[240:241]
	v_pk_fma_f32 v[242:243], v[166:167], v[46:47], v[242:243]
	v_pk_fma_f32 v[226:227], v[136:137], v[48:49], v[226:227]
	v_pk_fma_f32 v[228:229], v[140:141], v[48:49], v[228:229]
	v_pk_fma_f32 v[230:231], v[144:145], v[48:49], v[230:231]
	v_pk_fma_f32 v[232:233], v[148:149], v[48:49], v[232:233]
	v_pk_fma_f32 v[234:235], v[152:153], v[48:49], v[234:235]
	v_pk_fma_f32 v[236:237], v[156:157], v[48:49], v[236:237]
	v_pk_fma_f32 v[238:239], v[160:161], v[48:49], v[238:239]
	v_pk_fma_f32 v[240:241], v[164:165], v[48:49], v[240:241]
	v_pk_fma_f32 v[242:243], v[168:169], v[48:49], v[242:243]
	global_load_dword v34, v0, s[22:23]
	s_add_u32 s22, s22, 0x6000
	s_addc_u32 s23, s23, 0
	global_load_dword v35, v0, s[22:23]
	s_add_u32 s22, s22, 0x6000
	s_addc_u32 s23, s23, 0
	global_load_dword v36, v0, s[22:23]
	s_add_u32 s22, s22, 0x6000
	s_addc_u32 s23, s23, 0
	global_load_dword v37, v0, s[22:23]
	s_add_u32 s22, s22, 0x6000
	s_addc_u32 s23, s23, 0
	global_load_dword v38, v0, s[22:23]
	s_add_u32 s22, s22, 0x6000
	s_addc_u32 s23, s23, 0
	global_load_dword v39, v0, s[22:23]
	s_add_u32 s22, s22, 0x6000
	s_addc_u32 s23, s23, 0
	global_load_dword v40, v0, s[22:23]
	s_add_u32 s22, s22, 0x6000
	s_addc_u32 s23, s23, 0
	global_load_dword v41, v0, s[22:23]
	s_add_u32 s22, s22, 0x6000
	s_addc_u32 s23, s23, 0
	global_load_dword v42, v0, s[22:23]
	s_add_u32 s22, s22, 0x6000
	s_addc_u32 s23, s23, 0
	global_load_dword v43, v0, s[22:23]
	s_add_u32 s22, s22, 0x6000
	s_addc_u32 s23, s23, 0
	global_load_dword v44, v0, s[22:23]
	s_add_u32 s22, s22, 0x6000
	s_addc_u32 s23, s23, 0
	global_load_dword v45, v0, s[22:23]
	s_add_u32 s22, s22, 0x6000
	s_addc_u32 s23, s23, 0
	global_load_dword v46, v0, s[22:23]
	s_add_u32 s22, s22, 0x6000
	s_addc_u32 s23, s23, 0
	global_load_dword v47, v0, s[22:23]
	s_add_u32 s22, s22, 0x6000
	s_addc_u32 s23, s23, 0
	global_load_dword v48, v0, s[22:23]
	s_add_u32 s22, s22, 0x6000
	s_addc_u32 s23, s23, 0
	global_load_dword v49, v0, s[22:23]
	s_add_u32 s22, s22, 0x6000
	s_addc_u32 s23, s23, 0
	s_waitcnt vmcnt(16)
; #define LAS __attribute__((address_space(3)))
; __device__ __forceinline__ void prologue(const __attribute__((address_space(4))) Args& a, ldsp lds, int gw, int NGW, int wave, int lane, const int tid, const int bid, const int G) {
;     ...
;         for (int k = wave * 128; k < wave * 128 + 128; k += 16) {
;             float wv[16];
; #pragma unroll
;             for (int q = 0; q < 16; ++q) wv[q] = Wl[(size_t)(k + q) * NMOD];
; #pragma unroll
;             for (int q4 = 0; q4 < 4; ++q4)
; #pragma unroll
;                 for (int j = 0; j < 9; ++j) { const f32x4 s4 = *(const LAS f32x4*)(sc + j * D + k + 4 * q4); acc[j] += s4[0] * wv[4 * q4] + s4[1] * wv[4 * q4 + 1] + s4[2] * wv[4 * q4 + 2] + s4[3] * wv[4 * q4 + 3]; }
	ds_read_b128 v[134:137], v1 offset:400
	ds_read_b128 v[138:141], v1 offset:4496
	ds_read_b128 v[142:145], v1 offset:8592
	ds_read_b128 v[146:149], v1 offset:12688
	ds_read_b128 v[150:153], v1 offset:16784
	ds_read_b128 v[154:157], v1 offset:20880
	ds_read_b128 v[158:161], v1 offset:24976
	ds_read_b128 v[162:165], v1 offset:29072
	ds_read_b128 v[166:169], v1 offset:33168
	s_waitcnt lgkmcnt(9)
	v_pk_fma_f32 v[226:227], v[98:99], v[2:3], v[226:227]
	v_pk_fma_f32 v[228:229], v[102:103], v[2:3], v[228:229]
	v_pk_fma_f32 v[230:231], v[106:107], v[2:3], v[230:231]
	v_pk_fma_f32 v[232:233], v[110:111], v[2:3], v[232:233]
	v_pk_fma_f32 v[234:235], v[114:115], v[2:3], v[234:235]
	v_pk_fma_f32 v[236:237], v[118:119], v[2:3], v[236:237]
	v_pk_fma_f32 v[238:239], v[122:123], v[2:3], v[238:239]
	v_pk_fma_f32 v[240:241], v[126:127], v[2:3], v[240:241]
	v_pk_fma_f32 v[242:243], v[130:131], v[2:3], v[242:243]
	v_pk_fma_f32 v[226:227], v[100:101], v[4:5], v[226:227]
	v_pk_fma_f32 v[228:229], v[104:105], v[4:5], v[228:229]
	v_pk_fma_f32 v[230:231], v[108:109], v[4:5], v[230:231]
	v_pk_fma_f32 v[232:233], v[112:113], v[4:5], v[232:233]
	v_pk_fma_f32 v[234:235], v[116:117], v[4:5], v[234:235]
	v_pk_fma_f32 v[236:237], v[120:121], v[4:5], v[236:237]
	v_pk_fma_f32 v[238:239], v[124:125], v[4:5], v[238:239]
	v_pk_fma_f32 v[240:241], v[128:129], v[4:5], v[240:241]
	v_pk_fma_f32 v[242:243], v[132:133], v[4:5], v[242:243]
	ds_read_b128 v[98:101], v1 offset:416
	ds_read_b128 v[102:105], v1 offset:4512
	ds_read_b128 v[106:109], v1 offset:8608
	ds_read_b128 v[110:113], v1 offset:12704
	ds_read_b128 v[114:117], v1 offset:16800
	ds_read_b128 v[118:121], v1 offset:20896
	ds_read_b128 v[122:125], v1 offset:24992
	ds_read_b128 v[126:129], v1 offset:29088
	ds_read_b128 v[130:133], v1 offset:33184
	s_waitcnt lgkmcnt(9)
	v_pk_fma_f32 v[226:227], v[134:135], v[6:7], v[226:227]
	v_pk_fma_f32 v[228:229], v[138:139], v[6:7], v[228:229]
	v_pk_fma_f32 v[230:231], v[142:143], v[6:7], v[230:231]
	v_pk_fma_f32 v[232:233], v[146:147], v[6:7], v[232:233]
	v_pk_fma_f32 v[234:235], v[150:151], v[6:7], v[234:235]
	v_pk_fma_f32 v[236:237], v[154:155], v[6:7], v[236:237]
	v_pk_fma_f32 v[238:239], v[158:159], v[6:7], v[238:239]
	v_pk_fma_f32 v[240:241], v[162:163], v[6:7], v[240:241]
	v_pk_fma_f32 v[242:243], v[166:167], v[6:7], v[242:243]
	v_pk_fma_f32 v[226:227], v[136:137], v[8:9], v[226:227]
	v_pk_fma_f32 v[228:229], v[140:141], v[8:9], v[228:229]
	v_pk_fma_f32 v[230:231], v[144:145], v[8:9], v[230:231]
	v_pk_fma_f32 v[232:233], v[148:149], v[8:9], v[232:233]
	v_pk_fma_f32 v[234:235], v[152:153], v[8:9], v[234:235]
	v_pk_fma_f32 v[236:237], v[156:157], v[8:9], v[236:237]
	v_pk_fma_f32 v[238:239], v[160:161], v[8:9], v[238:239]
	v_pk_fma_f32 v[240:241], v[164:165], v[8:9], v[240:241]
	v_pk_fma_f32 v[242:243], v[168:169], v[8:9], v[242:243]
	ds_read_b128 v[134:137], v1 offset:432
	ds_read_b128 v[138:141], v1 offset:4528
	ds_read_b128 v[142:145], v1 offset:8624
	ds_read_b128 v[146:149], v1 offset:12720
	ds_read_b128 v[150:153], v1 offset:16816
	ds_read_b128 v[154:157], v1 offset:20912
	ds_read_b128 v[158:161], v1 offset:25008
	ds_read_b128 v[162:165], v1 offset:29104
	ds_read_b128 v[166:169], v1 offset:33200
	s_waitcnt lgkmcnt(9)
	v_pk_fma_f32 v[226:227], v[98:99], v[10:11], v[226:227]
	v_pk_fma_f32 v[228:229], v[102:103], v[10:11], v[228:229]
	v_pk_fma_f32 v[230:231], v[106:107], v[10:11], v[230:231]
	v_pk_fma_f32 v[232:233], v[110:111], v[10:11], v[232:233]
	v_pk_fma_f32 v[234:235], v[114:115], v[10:11], v[234:235]
	v_pk_fma_f32 v[236:237], v[118:119], v[10:11], v[236:237]
	v_pk_fma_f32 v[238:239], v[122:123], v[10:11], v[238:239]
	v_pk_fma_f32 v[240:241], v[126:127], v[10:11], v[240:241]
	v_pk_fma_f32 v[242:243], v[130:131], v[10:11], v[242:243]
	v_pk_fma_f32 v[226:227], v[100:101], v[12:13], v[226:227]
	v_pk_fma_f32 v[228:229], v[104:105], v[12:13], v[228:229]
	v_pk_fma_f32 v[230:231], v[108:109], v[12:13], v[230:231]
	v_pk_fma_f32 v[232:233], v[112:113], v[12:13], v[232:233]
	v_pk_fma_f32 v[234:235], v[116:117], v[12:13], v[234:235]
	v_pk_fma_f32 v[236:237], v[120:121], v[12:13], v[236:237]
	v_pk_fma_f32 v[238:239], v[124:125], v[12:13], v[238:239]
	v_pk_fma_f32 v[240:241], v[128:129], v[12:13], v[240:241]
	v_pk_fma_f32 v[242:243], v[132:133], v[12:13], v[242:243]
	ds_read_b128 v[98:101], v1 offset:448
	ds_read_b128 v[102:105], v1 offset:4544
	ds_read_b128 v[106:109], v1 offset:8640
	ds_read_b128 v[110:113], v1 offset:12736
	ds_read_b128 v[114:117], v1 offset:16832
	ds_read_b128 v[118:121], v1 offset:20928
	ds_read_b128 v[122:125], v1 offset:25024
	ds_read_b128 v[126:129], v1 offset:29120
	ds_read_b128 v[130:133], v1 offset:33216
	s_waitcnt lgkmcnt(9)
	v_pk_fma_f32 v[226:227], v[134:135], v[14:15], v[226:227]
	v_pk_fma_f32 v[228:229], v[138:139], v[14:15], v[228:229]
	v_pk_fma_f32 v[230:231], v[142:143], v[14:15], v[230:231]
	v_pk_fma_f32 v[232:233], v[146:147], v[14:15], v[232:233]
	v_pk_fma_f32 v[234:235], v[150:151], v[14:15], v[234:235]
	v_pk_fma_f32 v[236:237], v[154:155], v[14:15], v[236:237]
	v_pk_fma_f32 v[238:239], v[158:159], v[14:15], v[238:239]
	v_pk_fma_f32 v[240:241], v[162:163], v[14:15], v[240:241]
	v_pk_fma_f32 v[242:243], v[166:167], v[14:15], v[242:243]
	v_pk_fma_f32 v[226:227], v[136:137], v[16:17], v[226:227]
	v_pk_fma_f32 v[228:229], v[140:141], v[16:17], v[228:229]
	v_pk_fma_f32 v[230:231], v[144:145], v[16:17], v[230:231]
	v_pk_fma_f32 v[232:233], v[148:149], v[16:17], v[232:233]
	v_pk_fma_f32 v[234:235], v[152:153], v[16:17], v[234:235]
	v_pk_fma_f32 v[236:237], v[156:157], v[16:17], v[236:237]
	v_pk_fma_f32 v[238:239], v[160:161], v[16:17], v[238:239]
	v_pk_fma_f32 v[240:241], v[164:165], v[16:17], v[240:241]
	v_pk_fma_f32 v[242:243], v[168:169], v[16:17], v[242:243]
	s_waitcnt vmcnt(0)
; #define LAS __attribute__((address_space(3)))
; __device__ __forceinline__ void prologue(const __attribute__((address_space(4))) Args& a, ldsp lds, int gw, int NGW, int wave, int lane, const int tid, const int bid, const int G) {
;     ...
;         for (int k = wave * 128; k < wave * 128 + 128; k += 16) {
;             float wv[16];
; #pragma unroll
;             for (int q = 0; q < 16; ++q) wv[q] = Wl[(size_t)(k + q) * NMOD];
; #pragma unroll
;             for (int q4 = 0; q4 < 4; ++q4)
; #pragma unroll
;                 for (int j = 0; j < 9; ++j) { const f32x4 s4 = *(const LAS f32x4*)(sc + j * D + k + 4 * q4); acc[j] += s4[0] * wv[4 * q4] + s4[1] * wv[4 * q4 + 1] + s4[2] * wv[4 * q4 + 2] + s4[3] * wv[4 * q4 + 3]; }
;         }
; #pragma unroll
;         for (int j = 0; j < 9; ++j) red[(wave * 9 + j) * 64 + lane] = acc[j];
;         __syncthreads();
;         for (int i = tid; i < 9 * 64; i += 512) { const int j = i >> 6, cc = i & 63; float s = a.ada_b[layer * NMOD + col0 + cc];
; #pragma unroll
;             for (int w = 0; w < 8; ++w) s += red[(w * 9 + j) * 64 + cc];
	ds_read_b128 v[134:137], v1 offset:464
	ds_read_b128 v[138:141], v1 offset:4560
	ds_read_b128 v[142:145], v1 offset:8656
	ds_read_b128 v[146:149], v1 offset:12752
	ds_read_b128 v[150:153], v1 offset:16848
	ds_read_b128 v[154:157], v1 offset:20944
	ds_read_b128 v[158:161], v1 offset:25040
	ds_read_b128 v[162:165], v1 offset:29136
	ds_read_b128 v[166:169], v1 offset:33232
	s_waitcnt lgkmcnt(9)
	v_pk_fma_f32 v[226:227], v[98:99], v[34:35], v[226:227]
	v_pk_fma_f32 v[228:229], v[102:103], v[34:35], v[228:229]
	v_pk_fma_f32 v[230:231], v[106:107], v[34:35], v[230:231]
	v_pk_fma_f32 v[232:233], v[110:111], v[34:35], v[232:233]
	v_pk_fma_f32 v[234:235], v[114:115], v[34:35], v[234:235]
	v_pk_fma_f32 v[236:237], v[118:119], v[34:35], v[236:237]
	v_pk_fma_f32 v[238:239], v[122:123], v[34:35], v[238:239]
	v_pk_fma_f32 v[240:241], v[126:127], v[34:35], v[240:241]
	v_pk_fma_f32 v[242:243], v[130:131], v[34:35], v[242:243]
	v_pk_fma_f32 v[226:227], v[100:101], v[36:37], v[226:227]
	v_pk_fma_f32 v[228:229], v[104:105], v[36:37], v[228:229]
	v_pk_fma_f32 v[230:231], v[108:109], v[36:37], v[230:231]
	v_pk_fma_f32 v[232:233], v[112:113], v[36:37], v[232:233]
	v_pk_fma_f32 v[234:235], v[116:117], v[36:37], v[234:235]
	v_pk_fma_f32 v[236:237], v[120:121], v[36:37], v[236:237]
	v_pk_fma_f32 v[238:239], v[124:125], v[36:37], v[238:239]
	v_pk_fma_f32 v[240:241], v[128:129], v[36:37], v[240:241]
	v_pk_fma_f32 v[242:243], v[132:133], v[36:37], v[242:243]
	ds_read_b128 v[98:101], v1 offset:480
	ds_read_b128 v[102:105], v1 offset:4576
	ds_read_b128 v[106:109], v1 offset:8672
	ds_read_b128 v[110:113], v1 offset:12768
	ds_read_b128 v[114:117], v1 offset:16864
	ds_read_b128 v[118:121], v1 offset:20960
	ds_read_b128 v[122:125], v1 offset:25056
	ds_read_b128 v[126:129], v1 offset:29152
	ds_read_b128 v[130:133], v1 offset:33248
	s_waitcnt lgkmcnt(9)
	v_pk_fma_f32 v[226:227], v[134:135], v[38:39], v[226:227]
	v_pk_fma_f32 v[228:229], v[138:139], v[38:39], v[228:229]
	v_pk_fma_f32 v[230:231], v[142:143], v[38:39], v[230:231]
	v_pk_fma_f32 v[232:233], v[146:147], v[38:39], v[232:233]
	v_pk_fma_f32 v[234:235], v[150:151], v[38:39], v[234:235]
	v_pk_fma_f32 v[236:237], v[154:155], v[38:39], v[236:237]
	v_pk_fma_f32 v[238:239], v[158:159], v[38:39], v[238:239]
	v_pk_fma_f32 v[240:241], v[162:163], v[38:39], v[240:241]
	v_pk_fma_f32 v[242:243], v[166:167], v[38:39], v[242:243]
	v_pk_fma_f32 v[226:227], v[136:137], v[40:41], v[226:227]
	v_pk_fma_f32 v[228:229], v[140:141], v[40:41], v[228:229]
	v_pk_fma_f32 v[230:231], v[144:145], v[40:41], v[230:231]
	v_pk_fma_f32 v[232:233], v[148:149], v[40:41], v[232:233]
	v_pk_fma_f32 v[234:235], v[152:153], v[40:41], v[234:235]
	v_pk_fma_f32 v[236:237], v[156:157], v[40:41], v[236:237]
	v_pk_fma_f32 v[238:239], v[160:161], v[40:41], v[238:239]
	v_pk_fma_f32 v[240:241], v[164:165], v[40:41], v[240:241]
	v_pk_fma_f32 v[242:243], v[168:169], v[40:41], v[242:243]
	ds_read_b128 v[134:137], v1 offset:496
	ds_read_b128 v[138:141], v1 offset:4592
	ds_read_b128 v[142:145], v1 offset:8688
	ds_read_b128 v[146:149], v1 offset:12784
	ds_read_b128 v[150:153], v1 offset:16880
	ds_read_b128 v[154:157], v1 offset:20976
	ds_read_b128 v[158:161], v1 offset:25072
	ds_read_b128 v[162:165], v1 offset:29168
	ds_read_b128 v[166:169], v1 offset:33264
	s_waitcnt lgkmcnt(9)
	v_pk_fma_f32 v[226:227], v[98:99], v[42:43], v[226:227]
	v_pk_fma_f32 v[228:229], v[102:103], v[42:43], v[228:229]
	v_pk_fma_f32 v[230:231], v[106:107], v[42:43], v[230:231]
	v_pk_fma_f32 v[232:233], v[110:111], v[42:43], v[232:233]
	v_pk_fma_f32 v[234:235], v[114:115], v[42:43], v[234:235]
	v_pk_fma_f32 v[236:237], v[118:119], v[42:43], v[236:237]
	v_pk_fma_f32 v[238:239], v[122:123], v[42:43], v[238:239]
	v_pk_fma_f32 v[240:241], v[126:127], v[42:43], v[240:241]
	v_pk_fma_f32 v[242:243], v[130:131], v[42:43], v[242:243]
	v_pk_fma_f32 v[226:227], v[100:101], v[44:45], v[226:227]
	v_pk_fma_f32 v[228:229], v[104:105], v[44:45], v[228:229]
	v_pk_fma_f32 v[230:231], v[108:109], v[44:45], v[230:231]
	v_pk_fma_f32 v[232:233], v[112:113], v[44:45], v[232:233]
	v_pk_fma_f32 v[234:235], v[116:117], v[44:45], v[234:235]
	v_pk_fma_f32 v[236:237], v[120:121], v[44:45], v[236:237]
	v_pk_fma_f32 v[238:239], v[124:125], v[44:45], v[238:239]
	v_pk_fma_f32 v[240:241], v[128:129], v[44:45], v[240:241]
	v_pk_fma_f32 v[242:243], v[132:133], v[44:45], v[242:243]
	s_waitcnt lgkmcnt(0)
	v_pk_fma_f32 v[226:227], v[134:135], v[46:47], v[226:227]
	v_pk_fma_f32 v[228:229], v[138:139], v[46:47], v[228:229]
	v_pk_fma_f32 v[230:231], v[142:143], v[46:47], v[230:231]
	v_pk_fma_f32 v[232:233], v[146:147], v[46:47], v[232:233]
	v_pk_fma_f32 v[234:235], v[150:151], v[46:47], v[234:235]
	v_pk_fma_f32 v[236:237], v[154:155], v[46:47], v[236:237]
	v_pk_fma_f32 v[238:239], v[158:159], v[46:47], v[238:239]
	v_pk_fma_f32 v[240:241], v[162:163], v[46:47], v[240:241]
	v_pk_fma_f32 v[242:243], v[166:167], v[46:47], v[242:243]
	v_pk_fma_f32 v[226:227], v[136:137], v[48:49], v[226:227]
	v_pk_fma_f32 v[228:229], v[140:141], v[48:49], v[228:229]
	v_pk_fma_f32 v[230:231], v[144:145], v[48:49], v[230:231]
	v_pk_fma_f32 v[232:233], v[148:149], v[48:49], v[232:233]
	v_pk_fma_f32 v[234:235], v[152:153], v[48:49], v[234:235]
	v_pk_fma_f32 v[236:237], v[156:157], v[48:49], v[236:237]
	v_pk_fma_f32 v[238:239], v[160:161], v[48:49], v[238:239]
	v_pk_fma_f32 v[240:241], v[164:165], v[48:49], v[240:241]
	v_pk_fma_f32 v[242:243], v[168:169], v[48:49], v[242:243]
	v_add_f32_e32 v78, v226, v227
	v_add_f32_e32 v79, v228, v229
	v_add_f32_e32 v84, v230, v231
	v_add_f32_e32 v85, v232, v233
	v_add_f32_e32 v82, v234, v235
	v_add_f32_e32 v83, v236, v237
	v_add_f32_e32 v80, v238, v239
	v_add_f32_e32 v81, v240, v241
	v_add_f32_e32 v92, v242, v243
	ds_write2st64_b32 v91, v78, v79 offset1:1
	ds_write2st64_b32 v91, v84, v85 offset0:2 offset1:3
	ds_write2st64_b32 v91, v82, v83 offset0:4 offset1:5
	ds_write2st64_b32 v91, v80, v81 offset0:6 offset1:7
	ds_write_b32 v91, v92 offset:2048
	s_waitcnt lgkmcnt(0)
	s_barrier
	s_and_saveexec_b64 s[8:9], s[4:5]
	s_cbranch_execz .LBB0_1276
	s_mul_i32 s13, s12, 0x1800
	s_add_i32 s14, s13, s6
	v_or_b32_e32 v0, s14, v87
	v_ashrrev_i32_e32 v1, 31, v0
	s_mul_hi_i32 s13, s12, 9
	s_mul_i32 s12, s12, 9
	v_lshl_add_u64 v[0:1], v[0:1], 2, s[10:11]
	v_lshl_add_u64 v[2:3], s[6:7], 2, v[72:73]
	s_mov_b64 s[6:7], 0
	v_mov_b32_e32 v4, v196
